# Static priority raise (s_setprio 3) for the scanning wave 0 during the S5 chunk loop of the odd layers
# speedup vs baseline: 1.0019x; 1.0019x over previous
.LBB0_1090:
	s_setprio 3
	s_add_i32 s38, s2, 64
	s_and_b32 s38, s38, 64
	s_mul_i32 s39, s38, 0x210
	v_add_u32_e32 v66, s39, v126
	s_waitcnt vmcnt(0)
	ds_read2_b64 v[0:3], v66 offset1:66
	ds_read2_b64 v[4:7], v66 offset0:132 offset1:198
	s_mulk_i32 s38, 0x110
	v_add_u32_e32 v147, s38, v127
	v_add_u32_e32 v12, 0x800, v66
	s_waitcnt lgkmcnt(1)
	v_pk_fma_f32 v[0:1], v[62:63], v[122:123], v[0:1] op_sel:[0,1,0] op_sel_hi:[1,0,1]
	v_add_u32_e32 v152, 0x1000, v66
	v_pk_fma_f32 v[0:1], v[60:61], v[122:123], v[0:1]
	v_add_u32_e32 v160, 0x1800, v66
	v_pk_fma_f32 v[2:3], v[62:63], v[0:1], v[2:3] op_sel:[0,1,0] op_sel_hi:[1,0,1]
	v_cvt_pk_bf16_f32 v122, v0, v1
	v_pk_fma_f32 v[0:1], v[60:61], v[0:1], v[2:3]
	ds_read2_b64 v[8:11], v12 offset0:8 offset1:74
	ds_read2_b64 v[12:15], v12 offset0:140 offset1:206
	v_cvt_pk_bf16_f32 v2, v0, v1
	ds_read2_b64 v[148:151], v152 offset0:16 offset1:82
	ds_read2_b64 v[152:155], v152 offset0:148 offset1:214
	ds_read2_b64 v[156:159], v160 offset0:24 offset1:90
	ds_read2_b64 v[160:163], v160 offset0:156 offset1:222
	ds_write2_b32 v147, v122, v2 offset1:68
	s_waitcnt lgkmcnt(7)
	v_pk_fma_f32 v[2:3], v[62:63], v[0:1], v[4:5] op_sel:[0,1,0] op_sel_hi:[1,0,1]
	v_add_u32_e32 v5, 0x400, v147
	v_pk_fma_f32 v[0:1], v[60:61], v[0:1], v[2:3]
	s_nop 0
	v_pk_fma_f32 v[2:3], v[62:63], v[0:1], v[6:7] op_sel:[0,1,0] op_sel_hi:[1,0,1]
	v_cvt_pk_bf16_f32 v4, v0, v1
	v_pk_fma_f32 v[0:1], v[60:61], v[0:1], v[2:3]
	s_nop 0
	v_cvt_pk_bf16_f32 v2, v0, v1
	ds_write2_b32 v147, v4, v2 offset0:136 offset1:204
	s_waitcnt lgkmcnt(7)
	v_pk_fma_f32 v[2:3], v[62:63], v[0:1], v[8:9] op_sel:[0,1,0] op_sel_hi:[1,0,1]
	s_nop 0
	v_pk_fma_f32 v[0:1], v[60:61], v[0:1], v[2:3]
	s_nop 0
	v_pk_fma_f32 v[2:3], v[62:63], v[0:1], v[10:11] op_sel:[0,1,0] op_sel_hi:[1,0,1]
	v_cvt_pk_bf16_f32 v4, v0, v1
	v_pk_fma_f32 v[0:1], v[60:61], v[0:1], v[2:3]
	s_nop 0
	v_cvt_pk_bf16_f32 v2, v0, v1
	ds_write2_b32 v5, v4, v2 offset0:16 offset1:84
	s_waitcnt lgkmcnt(7)
	v_pk_fma_f32 v[2:3], v[62:63], v[0:1], v[12:13] op_sel:[0,1,0] op_sel_hi:[1,0,1]
	v_add_u32_e32 v12, 0x2800, v66
	v_pk_fma_f32 v[0:1], v[60:61], v[0:1], v[2:3]
	s_nop 0
	v_pk_fma_f32 v[2:3], v[62:63], v[0:1], v[14:15] op_sel:[0,1,0] op_sel_hi:[1,0,1]
	v_cvt_pk_bf16_f32 v4, v0, v1
	v_pk_fma_f32 v[0:1], v[60:61], v[0:1], v[2:3]
	s_nop 0
	v_cvt_pk_bf16_f32 v2, v0, v1
	ds_write2_b32 v5, v4, v2 offset0:152 offset1:220
	s_waitcnt lgkmcnt(7)
	v_pk_fma_f32 v[2:3], v[62:63], v[0:1], v[148:149] op_sel:[0,1,0] op_sel_hi:[1,0,1]
	v_add_u32_e32 v5, 0x800, v147
	v_pk_fma_f32 v[0:1], v[60:61], v[0:1], v[2:3]
	s_nop 0
	v_pk_fma_f32 v[2:3], v[62:63], v[0:1], v[150:151] op_sel:[0,1,0] op_sel_hi:[1,0,1]
	v_cvt_pk_bf16_f32 v4, v0, v1
	v_pk_fma_f32 v[0:1], v[60:61], v[0:1], v[2:3]
	s_nop 0
	v_cvt_pk_bf16_f32 v2, v0, v1
	ds_write2_b32 v5, v4, v2 offset0:32 offset1:100
	s_waitcnt lgkmcnt(7)
	v_pk_fma_f32 v[2:3], v[62:63], v[0:1], v[152:153] op_sel:[0,1,0] op_sel_hi:[1,0,1]
	v_add_u32_e32 v152, 0x3000, v66
	v_pk_fma_f32 v[0:1], v[60:61], v[0:1], v[2:3]
	s_nop 0
	v_pk_fma_f32 v[2:3], v[62:63], v[0:1], v[154:155] op_sel:[0,1,0] op_sel_hi:[1,0,1]
	v_cvt_pk_bf16_f32 v4, v0, v1
	v_pk_fma_f32 v[0:1], v[60:61], v[0:1], v[2:3]
	s_nop 0
	v_cvt_pk_bf16_f32 v2, v0, v1
	ds_write2_b32 v5, v4, v2 offset0:168 offset1:236
	s_waitcnt lgkmcnt(7)
	v_pk_fma_f32 v[2:3], v[62:63], v[0:1], v[156:157] op_sel:[0,1,0] op_sel_hi:[1,0,1]
	v_add_u32_e32 v5, 0xc00, v147
	v_pk_fma_f32 v[0:1], v[60:61], v[0:1], v[2:3]
	s_nop 0
	v_pk_fma_f32 v[2:3], v[62:63], v[0:1], v[158:159] op_sel:[0,1,0] op_sel_hi:[1,0,1]
	v_cvt_pk_bf16_f32 v4, v0, v1
	v_pk_fma_f32 v[0:1], v[60:61], v[0:1], v[2:3]
	s_nop 0
	v_cvt_pk_bf16_f32 v2, v0, v1
	ds_write2_b32 v5, v4, v2 offset0:48 offset1:116
	s_waitcnt lgkmcnt(7)
	v_pk_fma_f32 v[2:3], v[62:63], v[0:1], v[160:161] op_sel:[0,1,0] op_sel_hi:[1,0,1]
	v_add_u32_e32 v160, 0x3800, v66
	v_pk_fma_f32 v[0:1], v[60:61], v[0:1], v[2:3]
	s_nop 0
	v_pk_fma_f32 v[2:3], v[62:63], v[0:1], v[162:163] op_sel:[0,1,0] op_sel_hi:[1,0,1]
	v_cvt_pk_bf16_f32 v4, v0, v1
	v_pk_fma_f32 v[122:123], v[60:61], v[0:1], v[2:3]
	s_nop 0
	v_cvt_pk_bf16_f32 v0, v122, v123
	ds_write2_b32 v5, v4, v0 offset0:184 offset1:252
	v_add_u32_e32 v4, 0x2000, v66
	ds_read2_b64 v[0:3], v4 offset0:32 offset1:98
	ds_read2_b64 v[4:7], v4 offset0:164 offset1:230
	ds_read2_b64 v[8:11], v12 offset0:40 offset1:106
	ds_read2_b64 v[12:15], v12 offset0:172 offset1:238
	ds_read2_b64 v[148:151], v152 offset0:48 offset1:114
	ds_read2_b64 v[152:155], v152 offset0:180 offset1:246
	ds_read2_b64 v[156:159], v160 offset0:56 offset1:122
	ds_read2_b64 v[160:163], v160 offset0:188 offset1:254
	s_waitcnt lgkmcnt(7)
	v_pk_fma_f32 v[0:1], v[62:63], v[122:123], v[0:1] op_sel:[0,1,0] op_sel_hi:[1,0,1]
	s_nop 0
	v_pk_fma_f32 v[0:1], v[60:61], v[122:123], v[0:1]
	s_nop 0
	v_pk_fma_f32 v[2:3], v[62:63], v[0:1], v[2:3] op_sel:[0,1,0] op_sel_hi:[1,0,1]
	v_cvt_pk_bf16_f32 v122, v0, v1
	v_pk_fma_f32 v[0:1], v[60:61], v[0:1], v[2:3]
	v_add_u32_e32 v3, 0x1000, v147
	v_cvt_pk_bf16_f32 v2, v0, v1
	ds_write2_b32 v3, v122, v2 offset0:64 offset1:132
	s_waitcnt lgkmcnt(7)
	v_pk_fma_f32 v[2:3], v[62:63], v[0:1], v[4:5] op_sel:[0,1,0] op_sel_hi:[1,0,1]
	s_nop 0
	v_pk_fma_f32 v[0:1], v[60:61], v[0:1], v[2:3]
	s_nop 0
	v_pk_fma_f32 v[2:3], v[62:63], v[0:1], v[6:7] op_sel:[0,1,0] op_sel_hi:[1,0,1]
	v_cvt_pk_bf16_f32 v4, v0, v1
	v_pk_fma_f32 v[0:1], v[60:61], v[0:1], v[2:3]
	v_add_u32_e32 v3, 0x1200, v147
	v_cvt_pk_bf16_f32 v2, v0, v1
	ds_write2_b32 v3, v4, v2 offset0:72 offset1:140
	s_waitcnt lgkmcnt(7)
	v_pk_fma_f32 v[2:3], v[62:63], v[0:1], v[8:9] op_sel:[0,1,0] op_sel_hi:[1,0,1]
	v_add_u32_e32 v8, 0x4800, v66
	v_pk_fma_f32 v[0:1], v[60:61], v[0:1], v[2:3]
	s_nop 0
	v_pk_fma_f32 v[2:3], v[62:63], v[0:1], v[10:11] op_sel:[0,1,0] op_sel_hi:[1,0,1]
	v_cvt_pk_bf16_f32 v4, v0, v1
	v_pk_fma_f32 v[0:1], v[60:61], v[0:1], v[2:3]
	v_add_u32_e32 v3, 0x1400, v147
	v_cvt_pk_bf16_f32 v2, v0, v1
	ds_write2_b32 v3, v4, v2 offset0:80 offset1:148
	s_waitcnt lgkmcnt(7)
	v_pk_fma_f32 v[2:3], v[62:63], v[0:1], v[12:13] op_sel:[0,1,0] op_sel_hi:[1,0,1]
	ds_read2_b64 v[8:11], v8 offset0:72 offset1:138
	v_pk_fma_f32 v[0:1], v[60:61], v[0:1], v[2:3]
	v_add_u32_e32 v12, 0x4c00, v66
	v_pk_fma_f32 v[2:3], v[62:63], v[0:1], v[14:15] op_sel:[0,1,0] op_sel_hi:[1,0,1]
	v_cvt_pk_bf16_f32 v4, v0, v1
	v_pk_fma_f32 v[0:1], v[60:61], v[0:1], v[2:3]
	v_add_u32_e32 v3, 0x1600, v147
	v_cvt_pk_bf16_f32 v2, v0, v1
	ds_write2_b32 v3, v4, v2 offset0:88 offset1:156
	s_waitcnt lgkmcnt(8)
	v_pk_fma_f32 v[2:3], v[62:63], v[0:1], v[148:149] op_sel:[0,1,0] op_sel_hi:[1,0,1]
	ds_read2_b64 v[12:15], v12 offset0:76 offset1:142
	v_pk_fma_f32 v[0:1], v[60:61], v[0:1], v[2:3]
	v_add_u32_e32 v148, 0x5000, v66
	v_pk_fma_f32 v[2:3], v[62:63], v[0:1], v[150:151] op_sel:[0,1,0] op_sel_hi:[1,0,1]
	v_cvt_pk_bf16_f32 v4, v0, v1
	v_pk_fma_f32 v[0:1], v[60:61], v[0:1], v[2:3]
	v_add_u32_e32 v3, 0x1800, v147
	v_cvt_pk_bf16_f32 v2, v0, v1
	ds_write2_b32 v3, v4, v2 offset0:96 offset1:164
	s_waitcnt lgkmcnt(9)
	v_pk_fma_f32 v[2:3], v[62:63], v[0:1], v[152:153] op_sel:[0,1,0] op_sel_hi:[1,0,1]
	ds_read2_b64 v[148:151], v148 offset0:80 offset1:146
	v_pk_fma_f32 v[0:1], v[60:61], v[0:1], v[2:3]
	v_add_u32_e32 v152, 0x5400, v66
	v_pk_fma_f32 v[2:3], v[62:63], v[0:1], v[154:155] op_sel:[0,1,0] op_sel_hi:[1,0,1]
	v_cvt_pk_bf16_f32 v4, v0, v1
	v_pk_fma_f32 v[0:1], v[60:61], v[0:1], v[2:3]
	v_add_u32_e32 v3, 0x1a00, v147
	v_cvt_pk_bf16_f32 v2, v0, v1
	ds_write2_b32 v3, v4, v2 offset0:104 offset1:172
	s_waitcnt lgkmcnt(10)
	v_pk_fma_f32 v[2:3], v[62:63], v[0:1], v[156:157] op_sel:[0,1,0] op_sel_hi:[1,0,1]
	ds_read2_b64 v[152:155], v152 offset0:84 offset1:150
	v_pk_fma_f32 v[0:1], v[60:61], v[0:1], v[2:3]
	v_add_u32_e32 v156, 0x5800, v66
	v_pk_fma_f32 v[2:3], v[62:63], v[0:1], v[158:159] op_sel:[0,1,0] op_sel_hi:[1,0,1]
	v_cvt_pk_bf16_f32 v4, v0, v1
	v_pk_fma_f32 v[0:1], v[60:61], v[0:1], v[2:3]
	v_add_u32_e32 v3, 0x1c00, v147
	v_cvt_pk_bf16_f32 v2, v0, v1
	ds_write2_b32 v3, v4, v2 offset0:112 offset1:180
	s_waitcnt lgkmcnt(11)
	v_pk_fma_f32 v[2:3], v[62:63], v[0:1], v[160:161] op_sel:[0,1,0] op_sel_hi:[1,0,1]
	ds_read2_b64 v[156:159], v156 offset0:88 offset1:154
	v_pk_fma_f32 v[0:1], v[60:61], v[0:1], v[2:3]
	v_add_u32_e32 v160, 0x5c00, v66
	v_pk_fma_f32 v[2:3], v[62:63], v[0:1], v[162:163] op_sel:[0,1,0] op_sel_hi:[1,0,1]
	v_cvt_pk_bf16_f32 v4, v0, v1
	v_pk_fma_f32 v[122:123], v[60:61], v[0:1], v[2:3]
	v_add_u32_e32 v1, 0x1e00, v147
	v_cvt_pk_bf16_f32 v0, v122, v123
	ds_write2_b32 v1, v4, v0 offset0:120 offset1:188
	v_add_u32_e32 v0, 0x4000, v66
	ds_read2_b64 v[0:3], v0 offset0:64 offset1:130
	v_add_u32_e32 v4, 0x4400, v66
	ds_read2_b64 v[4:7], v4 offset0:68 offset1:134
	ds_read2_b64 v[160:163], v160 offset0:92 offset1:158
	s_waitcnt lgkmcnt(2)
	v_pk_fma_f32 v[0:1], v[62:63], v[122:123], v[0:1] op_sel:[0,1,0] op_sel_hi:[1,0,1]
	s_nop 0
	v_pk_fma_f32 v[0:1], v[60:61], v[122:123], v[0:1]
	s_nop 0
	v_pk_fma_f32 v[2:3], v[62:63], v[0:1], v[2:3] op_sel:[0,1,0] op_sel_hi:[1,0,1]
	v_cvt_pk_bf16_f32 v122, v0, v1
	v_pk_fma_f32 v[0:1], v[60:61], v[0:1], v[2:3]
	v_add_u32_e32 v3, 0x2000, v147
	v_cvt_pk_bf16_f32 v2, v0, v1
	ds_write2_b32 v3, v122, v2 offset0:128 offset1:196
	s_waitcnt lgkmcnt(2)
	v_pk_fma_f32 v[2:3], v[62:63], v[0:1], v[4:5] op_sel:[0,1,0] op_sel_hi:[1,0,1]
	v_add_u32_e32 v5, 0x2400, v147
	v_pk_fma_f32 v[0:1], v[60:61], v[0:1], v[2:3]
	s_nop 0
	v_pk_fma_f32 v[2:3], v[62:63], v[0:1], v[6:7] op_sel:[0,1,0] op_sel_hi:[1,0,1]
	v_cvt_pk_bf16_f32 v4, v0, v1
	v_pk_fma_f32 v[0:1], v[60:61], v[0:1], v[2:3]
	s_nop 0
	v_cvt_pk_bf16_f32 v2, v0, v1
	ds_write2_b32 v5, v4, v2 offset0:8 offset1:76
	v_pk_fma_f32 v[2:3], v[62:63], v[0:1], v[8:9] op_sel:[0,1,0] op_sel_hi:[1,0,1]
	v_add_u32_e32 v8, 0x6800, v66
	v_pk_fma_f32 v[0:1], v[60:61], v[0:1], v[2:3]
	s_nop 0
	v_pk_fma_f32 v[2:3], v[62:63], v[0:1], v[10:11] op_sel:[0,1,0] op_sel_hi:[1,0,1]
	v_cvt_pk_bf16_f32 v4, v0, v1
	v_pk_fma_f32 v[0:1], v[60:61], v[0:1], v[2:3]
	ds_read2_b64 v[8:11], v8 offset0:104 offset1:170
	v_cvt_pk_bf16_f32 v2, v0, v1
	ds_write2_b32 v5, v4, v2 offset0:144 offset1:212
	v_pk_fma_f32 v[2:3], v[62:63], v[0:1], v[12:13] op_sel:[0,1,0] op_sel_hi:[1,0,1]
	v_add_u32_e32 v5, 0x2800, v147
	v_pk_fma_f32 v[0:1], v[60:61], v[0:1], v[2:3]
	v_add_u32_e32 v12, 0x6c00, v66
	v_pk_fma_f32 v[2:3], v[62:63], v[0:1], v[14:15] op_sel:[0,1,0] op_sel_hi:[1,0,1]
	v_cvt_pk_bf16_f32 v4, v0, v1
	v_pk_fma_f32 v[0:1], v[60:61], v[0:1], v[2:3]
	ds_read2_b64 v[12:15], v12 offset0:108 offset1:174
	v_cvt_pk_bf16_f32 v2, v0, v1
	ds_write2_b32 v5, v4, v2 offset0:24 offset1:92
	v_pk_fma_f32 v[2:3], v[62:63], v[0:1], v[148:149] op_sel:[0,1,0] op_sel_hi:[1,0,1]
	v_add_u32_e32 v148, 0x7000, v66
	v_pk_fma_f32 v[0:1], v[60:61], v[0:1], v[2:3]
	s_nop 0
	v_pk_fma_f32 v[2:3], v[62:63], v[0:1], v[150:151] op_sel:[0,1,0] op_sel_hi:[1,0,1]
	v_cvt_pk_bf16_f32 v4, v0, v1
	v_pk_fma_f32 v[0:1], v[60:61], v[0:1], v[2:3]
	ds_read2_b64 v[148:151], v148 offset0:112 offset1:178
	v_cvt_pk_bf16_f32 v2, v0, v1
	ds_write2_b32 v5, v4, v2 offset0:160 offset1:228
	v_pk_fma_f32 v[2:3], v[62:63], v[0:1], v[152:153] op_sel:[0,1,0] op_sel_hi:[1,0,1]
	v_add_u32_e32 v5, 0x2c00, v147
	v_pk_fma_f32 v[0:1], v[60:61], v[0:1], v[2:3]
	v_add_u32_e32 v152, 0x7400, v66
	v_pk_fma_f32 v[2:3], v[62:63], v[0:1], v[154:155] op_sel:[0,1,0] op_sel_hi:[1,0,1]
	v_cvt_pk_bf16_f32 v4, v0, v1
	v_pk_fma_f32 v[0:1], v[60:61], v[0:1], v[2:3]
	ds_read2_b64 v[152:155], v152 offset0:116 offset1:182
	v_cvt_pk_bf16_f32 v2, v0, v1
	ds_write2_b32 v5, v4, v2 offset0:40 offset1:108
	v_pk_fma_f32 v[2:3], v[62:63], v[0:1], v[156:157] op_sel:[0,1,0] op_sel_hi:[1,0,1]
	v_add_u32_e32 v156, 0x7800, v66
	v_pk_fma_f32 v[0:1], v[60:61], v[0:1], v[2:3]
	s_nop 0
	v_pk_fma_f32 v[2:3], v[62:63], v[0:1], v[158:159] op_sel:[0,1,0] op_sel_hi:[1,0,1]
	v_cvt_pk_bf16_f32 v4, v0, v1
	v_pk_fma_f32 v[0:1], v[60:61], v[0:1], v[2:3]
	ds_read2_b64 v[156:159], v156 offset0:120 offset1:186
	v_cvt_pk_bf16_f32 v2, v0, v1
	ds_write2_b32 v5, v4, v2 offset0:176 offset1:244
	s_waitcnt lgkmcnt(12)
	v_pk_fma_f32 v[2:3], v[62:63], v[0:1], v[160:161] op_sel:[0,1,0] op_sel_hi:[1,0,1]
	s_nop 0
	v_pk_fma_f32 v[0:1], v[60:61], v[0:1], v[2:3]
	s_nop 0
	v_pk_fma_f32 v[2:3], v[62:63], v[0:1], v[162:163] op_sel:[0,1,0] op_sel_hi:[1,0,1]
	v_cvt_pk_bf16_f32 v4, v0, v1
	v_pk_fma_f32 v[122:123], v[60:61], v[0:1], v[2:3]
	v_add_u32_e32 v1, 0x3000, v147
	v_cvt_pk_bf16_f32 v0, v122, v123
	ds_write2_b32 v1, v4, v0 offset0:56 offset1:124
	v_add_u32_e32 v0, 0x6000, v66
	ds_read2_b64 v[0:3], v0 offset0:96 offset1:162
	v_add_u32_e32 v4, 0x6400, v66
	ds_read2_b64 v[4:7], v4 offset0:100 offset1:166
	v_add_u32_e32 v66, 0x7c00, v66
	ds_read2_b64 v[160:163], v66 offset0:124 offset1:190
	s_waitcnt lgkmcnt(2)
	v_pk_fma_f32 v[0:1], v[62:63], v[122:123], v[0:1] op_sel:[0,1,0] op_sel_hi:[1,0,1]
	s_nop 0
	v_pk_fma_f32 v[0:1], v[60:61], v[122:123], v[0:1]
	s_nop 0
	v_pk_fma_f32 v[2:3], v[62:63], v[0:1], v[2:3] op_sel:[0,1,0] op_sel_hi:[1,0,1]
	v_cvt_pk_bf16_f32 v66, v0, v1
	v_pk_fma_f32 v[0:1], v[60:61], v[0:1], v[2:3]
	v_add_u32_e32 v3, 0x3200, v147
	v_cvt_pk_bf16_f32 v2, v0, v1
	ds_write2_b32 v3, v66, v2 offset0:64 offset1:132
	s_waitcnt lgkmcnt(2)
	v_pk_fma_f32 v[2:3], v[62:63], v[0:1], v[4:5] op_sel:[0,1,0] op_sel_hi:[1,0,1]
	s_nop 0
	v_pk_fma_f32 v[0:1], v[60:61], v[0:1], v[2:3]
	s_nop 0
	v_pk_fma_f32 v[2:3], v[62:63], v[0:1], v[6:7] op_sel:[0,1,0] op_sel_hi:[1,0,1]
	v_cvt_pk_bf16_f32 v4, v0, v1
	v_pk_fma_f32 v[0:1], v[60:61], v[0:1], v[2:3]
	v_add_u32_e32 v3, 0x3400, v147
	v_cvt_pk_bf16_f32 v2, v0, v1
	ds_write2_b32 v3, v4, v2 offset0:72 offset1:140
	v_pk_fma_f32 v[2:3], v[62:63], v[0:1], v[8:9] op_sel:[0,1,0] op_sel_hi:[1,0,1]
	s_nop 0
	v_pk_fma_f32 v[0:1], v[60:61], v[0:1], v[2:3]
	s_nop 0
	v_pk_fma_f32 v[2:3], v[62:63], v[0:1], v[10:11] op_sel:[0,1,0] op_sel_hi:[1,0,1]
	v_cvt_pk_bf16_f32 v4, v0, v1
	v_pk_fma_f32 v[0:1], v[60:61], v[0:1], v[2:3]
	v_add_u32_e32 v3, 0x3600, v147
	v_cvt_pk_bf16_f32 v2, v0, v1
	ds_write2_b32 v3, v4, v2 offset0:80 offset1:148
	v_pk_fma_f32 v[2:3], v[62:63], v[0:1], v[12:13] op_sel:[0,1,0] op_sel_hi:[1,0,1]
	s_nop 0
	v_pk_fma_f32 v[0:1], v[60:61], v[0:1], v[2:3]
	s_nop 0
	v_pk_fma_f32 v[2:3], v[62:63], v[0:1], v[14:15] op_sel:[0,1,0] op_sel_hi:[1,0,1]
	v_cvt_pk_bf16_f32 v4, v0, v1
	v_pk_fma_f32 v[0:1], v[60:61], v[0:1], v[2:3]
	v_add_u32_e32 v3, 0x3800, v147
	v_cvt_pk_bf16_f32 v2, v0, v1
	ds_write2_b32 v3, v4, v2 offset0:88 offset1:156
	v_pk_fma_f32 v[2:3], v[62:63], v[0:1], v[148:149] op_sel:[0,1,0] op_sel_hi:[1,0,1]
	s_nop 0
	v_pk_fma_f32 v[0:1], v[60:61], v[0:1], v[2:3]
	s_nop 0
	v_pk_fma_f32 v[2:3], v[62:63], v[0:1], v[150:151] op_sel:[0,1,0] op_sel_hi:[1,0,1]
	v_cvt_pk_bf16_f32 v4, v0, v1
	v_pk_fma_f32 v[0:1], v[60:61], v[0:1], v[2:3]
	v_add_u32_e32 v3, 0x3a00, v147
	v_cvt_pk_bf16_f32 v2, v0, v1
	ds_write2_b32 v3, v4, v2 offset0:96 offset1:164
	v_pk_fma_f32 v[2:3], v[62:63], v[0:1], v[152:153] op_sel:[0,1,0] op_sel_hi:[1,0,1]
	s_nop 0
	v_pk_fma_f32 v[0:1], v[60:61], v[0:1], v[2:3]
	s_nop 0
	v_pk_fma_f32 v[2:3], v[62:63], v[0:1], v[154:155] op_sel:[0,1,0] op_sel_hi:[1,0,1]
	v_cvt_pk_bf16_f32 v4, v0, v1
	v_pk_fma_f32 v[0:1], v[60:61], v[0:1], v[2:3]
	v_add_u32_e32 v3, 0x3c00, v147
	v_cvt_pk_bf16_f32 v2, v0, v1
	ds_write2_b32 v3, v4, v2 offset0:104 offset1:172
	v_pk_fma_f32 v[2:3], v[62:63], v[0:1], v[156:157] op_sel:[0,1,0] op_sel_hi:[1,0,1]
	s_nop 0
	v_pk_fma_f32 v[0:1], v[60:61], v[0:1], v[2:3]
	s_nop 0
	v_pk_fma_f32 v[2:3], v[62:63], v[0:1], v[158:159] op_sel:[0,1,0] op_sel_hi:[1,0,1]
	v_cvt_pk_bf16_f32 v4, v0, v1
	v_pk_fma_f32 v[0:1], v[60:61], v[0:1], v[2:3]
	v_add_u32_e32 v3, 0x3e00, v147
	v_cvt_pk_bf16_f32 v2, v0, v1
	ds_write2_b32 v3, v4, v2 offset0:112 offset1:180
	s_waitcnt lgkmcnt(7)
	v_pk_fma_f32 v[2:3], v[62:63], v[0:1], v[160:161] op_sel:[0,1,0] op_sel_hi:[1,0,1]
	s_nop 0
	v_pk_fma_f32 v[0:1], v[60:61], v[0:1], v[2:3]
	s_nop 0
	v_pk_fma_f32 v[2:3], v[62:63], v[0:1], v[162:163] op_sel:[0,1,0] op_sel_hi:[1,0,1]
	v_cvt_pk_bf16_f32 v4, v0, v1
	v_pk_fma_f32 v[122:123], v[60:61], v[0:1], v[2:3]
	v_add_u32_e32 v1, 0x4000, v147
	v_cvt_pk_bf16_f32 v0, v122, v123
	ds_write2_b32 v1, v4, v0 offset0:120 offset1:188

.LBB0_1109:
	s_setprio 0
	s_andn2_b64 vcc, exec, s[26:27]
	s_cbranch_vccnz .LBB0_1050
	ds_read_b128 v[0:3], v133
	ds_read_b128 v[4:7], v133 offset:64
	ds_read_b128 v[8:11], v133 offset:128
	ds_read_b128 v[12:15], v133 offset:192
	s_waitcnt lgkmcnt(3)
	v_mfma_f32_16x16x32_bf16 v[0:3], v[0:3], v[48:51], 0
	v_mov_b32_e32 v49, s37
	v_or_b32_e32 v48, s36, v88
	s_waitcnt lgkmcnt(2)
	v_mfma_f32_16x16x32_bf16 v[0:3], v[4:7], v[44:47], v[0:3]
	v_lshlrev_b32_e32 v44, 16, v143
	v_and_b32_e32 v45, 0xffff0000, v143
	v_lshlrev_b32_e32 v46, 16, v107
	s_waitcnt lgkmcnt(1)
	v_mfma_f32_16x16x32_bf16 v[0:3], v[8:11], v[40:43], v[0:3]
	v_lshlrev_b64 v[4:5], 10, v[48:49]
	v_lshl_add_u64 v[6:7], v[110:111], 0, v[4:5]
	v_or_b32_e32 v8, 0x400, v4
	s_waitcnt lgkmcnt(0)
	v_mfma_f32_16x16x32_bf16 v[0:3], v[12:15], v[36:39], v[0:3]
	s_nop 7
	v_fma_f32 v0, v142, v44, v0
	v_mul_f32_e32 v9, 0x3d372713, v0
	v_mul_f32_e32 v9, v0, v9
	v_fma_f32 v1, v142, v45, v1
	v_fma_f32 v9, v0, v9, v0
	v_mul_f32_e32 v10, 0x3d372713, v1
	v_mul_f32_e32 v9, 0xbfcc422a, v9
	v_mul_f32_e32 v10, v1, v10
	v_mul_f32_e32 v9, 0x3fb8aa3b, v9
	v_fma_f32 v10, v1, v10, v1
	v_exp_f32_e32 v9, v9
	v_mul_f32_e32 v10, 0xbfcc422a, v10
	v_mul_f32_e32 v10, 0x3fb8aa3b, v10
	v_exp_f32_e32 v10, v10
	v_add_f32_e32 v9, 1.0, v9
	v_rcp_f32_e32 v9, v9
	v_fma_f32 v2, v142, v46, v2
	v_add_f32_e32 v10, 1.0, v10
	v_mul_f32_e32 v11, 0x3d372713, v2
	v_rcp_f32_e32 v10, v10
	v_mul_f32_e32 v11, v2, v11
	v_mul_f32_e32 v0, v0, v9
	v_fma_f32 v11, v2, v11, v2
	v_cvt_pk_bf16_f32 v0, v0, s0
	global_store_short v[6:7], v0, off
	v_mul_f32_e32 v0, 0xbfcc422a, v11
	v_mul_f32_e32 v1, v1, v10
	v_mul_f32_e32 v0, 0x3fb8aa3b, v0
	v_mov_b32_e32 v9, v5
	v_cvt_pk_bf16_f32 v10, v1, s0
	v_exp_f32_e32 v6, v0
	v_lshl_add_u64 v[0:1], v[110:111], 0, v[8:9]
	global_store_short v[0:1], v10, off
	v_and_b32_e32 v1, 0xffff0000, v107
	v_fmac_f32_e32 v3, v142, v1
	v_mul_f32_e32 v1, 0x3d372713, v3
	v_mul_f32_e32 v1, v3, v1
	v_fma_f32 v1, v3, v1, v3
	v_mul_f32_e32 v1, 0xbfcc422a, v1
	v_mul_f32_e32 v1, 0x3fb8aa3b, v1
	v_exp_f32_e32 v1, v1
	v_add_f32_e32 v0, 1.0, v6
	v_rcp_f32_e32 v0, v0
	v_add_f32_e32 v1, 1.0, v1
	v_rcp_f32_e32 v6, v1
	v_mul_f32_e32 v0, v2, v0
	v_cvt_pk_bf16_f32 v2, v0, s0
	v_or_b32_e32 v0, 0x800, v4
	v_mov_b32_e32 v1, v5
	v_lshl_add_u64 v[0:1], v[110:111], 0, v[0:1]
	global_store_short v[0:1], v2, off
	v_mul_f32_e32 v0, v3, v6
	v_or_b32_e32 v4, 0xc00, v4
	v_cvt_pk_bf16_f32 v2, v0, s0
	v_lshl_add_u64 v[0:1], v[110:111], 0, v[4:5]
	global_store_short v[0:1], v2, off
	s_branch .LBB0_1050
